# attention step loop back-edge rotation: next K/V tile address math and global loads moved from the post-barrier head to the tail
# speedup vs baseline: 1.0045x; 1.0037x over previous
; __device__ void attn_item(const Params& p, char* lds, int bh, int qi) {
;     ...
;   f32x16 O[2];
; #pragma unroll
;   for (int d = 0; d < 2; ++d)
; #pragma unroll
;     for (int r = 0; r < 16; ++r) O[d][r] = 0.f;
;   float mref = 0.f, lsum = 0.f;
;   bool first = true;
;   const int nsteps = (qi + 1) * 4;
;   const int skey = tid >> 3, sch = tid & 7;
;   u32x4 rk, rv;
;   auto gload = [&](int s) {
;     const int jb = qi - (s >> 2), sub = s & 3, key0 = jb * 256 + sub * 64;
;     rk = *(const u32x4*)(Kg + (size_t)(key0 + skey) * 64 + sch * 8);
;     rv = *(const u32x4*)(Vg + (size_t)skey * SEQ + key0 + sch * 8);
;   };
;   auto swrite = [&](int buf) {
;     *(u32x4*)(Ks + buf * 64 * LD + skey * LD + sch * 8) = rk;
;     u16* vd = Vs + buf * 64 * LD + skey * LD + 16 * (sch >> 1) + 4 * (sch & 1);
;     u32x2 a, b; a.x = rv.x; a.y = rv.y; b.x = rv.z; b.y = rv.w;
;     *(u32x2*)(vd) = a;
;     *(u32x2*)(vd + 8) = b;
;   };
;   gload(0); swrite(0);
;   __syncthreads();
;     ...
;   for (int s = 0; s < nsteps; ++s) {
;     if (s + 1 < nsteps) gload(s + 1);
;     const int jb = qi - (s >> 2), sub = s & 3;
;     const bool own = (s < 4);
;     const bool sel = own ? true : ((selmask >> jb) & 1u);
;     bool active;
;     if (own) active = (sub * 64 <= wave * 32 + 31);
;     else active = (__ballot(sel) != 0ull);
.LBB0_414:
	s_lshl_b32 s5, s22, 18
	s_lshl_b32 s5, s5, 1
	s_add_u32 s18, s10, s5
	v_or_b32_e32 v2, s4, v240
	v_mov_b32_e32 v3, v95
	v_lshl_add_u64 v[18:19], v[96:97], 0, s[6:7]
	s_mov_b32 s5, s7
	s_addc_u32 s19, s11, 0
	v_lshlrev_b64 v[2:3], 7, v[2:3]
	v_mov_b32_e32 v107, v95
	v_lshl_add_u64 v[4:5], s[4:5], 1, v[18:19]
	v_lshl_add_u64 v[2:3], s[18:19], 0, v[2:3]
	v_lshl_add_u64 v[4:5], v[4:5], 0, v[106:107]
	v_lshl_add_u64 v[2:3], v[2:3], 0, v[106:107]
	global_load_dwordx4 v[86:89], v[4:5], off
	global_load_dwordx4 v[82:85], v[2:3], off
	v_mov_b32_e32 v16, v95
	v_mov_b32_e32 v17, v95
	v_mov_b32_e32 v2, v95
	v_mov_b32_e32 v3, v95
	v_mov_b32_e32 v4, v95
	v_mov_b32_e32 v5, v95
	v_mov_b32_e32 v6, v95
	v_mov_b32_e32 v7, v95
	v_mov_b32_e32 v8, v95
	v_mov_b32_e32 v9, v95
	v_mov_b32_e32 v10, v95
	v_mov_b32_e32 v11, v95
	v_mov_b32_e32 v12, v95
	v_mov_b32_e32 v13, v95
	v_mov_b32_e32 v14, v95
	v_mov_b32_e32 v15, v95
	v_lshl_add_u64 v[108:109], v[18:19], 0, v[106:107]
	v_mov_b64_e32 v[32:33], v[16:17]
	s_lshl_b32 s38, s37, 2
	v_add_u32_e32 v34, 0x4800, v117
	s_mov_b32 s6, 0
	s_mov_b64 s[14:15], -1
	v_mov_b32_e32 v126, 0
	s_mov_b32 s26, 0
	v_mov_b64_e32 v[30:31], v[14:15]
	v_mov_b64_e32 v[28:29], v[12:13]
	v_mov_b64_e32 v[26:27], v[10:11]
	v_mov_b64_e32 v[24:25], v[8:9]
	v_mov_b64_e32 v[22:23], v[6:7]
	v_mov_b64_e32 v[20:21], v[4:5]
	v_mov_b64_e32 v[18:19], v[2:3]
	s_add_i32 s38, s38, 4
	v_lshl_add_u64 v[110:111], s[18:19], 0, v[106:107]
	v_mov_b32_e32 v107, 0
	s_waitcnt vmcnt(1)
	ds_write2_b64 v34, v[86:87], v[88:89] offset1:2
	s_waitcnt vmcnt(0)
	ds_write_b128 v116, v[82:85]
	s_lshl_b32 s20, s37, 8
	s_or_b32 s20, s20, 64
	v_add_u32_e32 v34, s20, v240
	v_ashrrev_i32_e32 v35, 31, v34
	v_lshlrev_b64 v[34:35], 7, v[34:35]
	v_lshl_add_u64 v[34:35], v[110:111], 0, v[34:35]
	s_ashr_i32 s21, s20, 31
	global_load_dwordx4 v[82:85], v[34:35], off
	v_lshl_add_u64 v[34:35], s[20:21], 1, v[108:109]
	global_load_dwordx4 v[86:89], v[34:35], off
	s_waitcnt lgkmcnt(0)
	s_barrier
.LBB0_415:
	s_add_i32 s39, s26, 1
	s_cmp_lt_u32 s39, s38
	s_cselect_b64 s[18:19], -1, 0
.LBB0_417:
	s_lshr_b32 s4, s26, 2
	s_sub_i32 s4, s37, s4
	v_lshrrev_b32_e32 v34, s4, v105
	s_cmp_lt_u32 s26, 4
	v_and_b32_e32 v34, 1, v34
	s_cselect_b64 s[22:23], -1, 0
	s_cmp_gt_u32 s26, 3
	v_cmp_eq_u32_e64 s[4:5], 1, v34
	s_mov_b64 s[20:21], -1
	s_cbranch_scc0 .LBB0_419
	v_cndmask_b32_e64 v34, 0, 1, s[4:5]
	v_cmp_ne_u32_e32 vcc, 0, v34
	s_cmp_lg_u64 vcc, 0
	s_mov_b64 s[20:21], 0
	s_cselect_b64 s[28:29], -1, 0

; __device__ void attn_item(const Params& p, char* lds, int bh, int qi) {
;     ...
;   for (int s = 0; s < nsteps; ++s) {
;     if (s + 1 < nsteps) gload(s + 1);
;     ...
;     if (s + 1 < nsteps) swrite((s + 1) & 1);
;     __syncthreads();
;   }
.LBB0_424:
	s_bitcmp1_b32 s39, 0
	s_cselect_b32 s14, 0x2400, 0
	v_add_u32_e32 v34, s14, v116
	v_add_u32_e32 v35, s14, v117
	s_waitcnt vmcnt(1)
	ds_write_b128 v34, v[82:85]
	v_add_u32_e32 v34, 0x4800, v35
	s_waitcnt vmcnt(0)
	ds_write2_b64 v34, v[86:87], v[88:89] offset1:2
	s_add_i32 s14, s39, 1
	s_cmp_ge_u32 s14, s38
	s_cbranch_scc1 .Lattn_nogl
	s_lshr_b32 s20, s14, 2
	s_sub_i32 s20, s37, s20
	s_lshl_b32 s20, s20, 8
	s_lshl_b32 s21, s14, 6
	s_and_b32 s21, s21, 0xc0
	s_or_b32 s20, s20, s21
	v_add_u32_e32 v34, s20, v240
	v_ashrrev_i32_e32 v35, 31, v34
	v_lshlrev_b64 v[34:35], 7, v[34:35]
	v_lshl_add_u64 v[34:35], v[110:111], 0, v[34:35]
	s_ashr_i32 s21, s20, 31
	global_load_dwordx4 v[82:85], v[34:35], off
	v_lshl_add_u64 v[34:35], s[20:21], 1, v[108:109]
	global_load_dwordx4 v[86:89], v[34:35], off
.Lattn_nogl:
.LBB0_425:
	s_add_i32 s6, s6, 64
	s_cmp_lg_u32 s38, s39
	s_waitcnt lgkmcnt(0)
	s_barrier
	s_cbranch_scc0 .LBB0_392
	s_mov_b64 s[14:15], s[4:5]
	s_mov_b32 s26, s39
	s_branch .LBB0_415
